# grid barrier: per-XCD election kept, release = cross-XCD arrival counter reaching (gen+1)*nx, polled by leaders and non-leaders alike; no release word, no per-XCD generation write
# speedup vs baseline: 1.0022x; 1.0022x over previous
.LBB0_73:
	s_or_b64 exec, exec, s[10:11]
	v_cvt_f32_u32_e32 v4, v2
	s_waitcnt vmcnt(0)
	v_readfirstlane_b32 s3, v3
	v_sub_u32_e32 v3, 0, v2
	v_rcp_iflag_f32_e32 v4, v4
	v_add_u32_e32 v5, s3, v1
	v_mul_f32_e32 v4, 0x4f7ffffe, v4
	v_cvt_u32_f32_e32 v4, v4
	v_mul_lo_u32 v1, v3, v4
	v_mul_hi_u32 v1, v4, v1
	v_add_u32_e32 v1, v4, v1
	v_mul_hi_u32 v1, v5, v1
	v_mul_lo_u32 v3, v1, v2
	v_sub_u32_e32 v3, v5, v3
	v_add_u32_e32 v4, 1, v1
	v_cmp_ge_u32_e32 vcc, v3, v2
	s_nop 1
	v_cndmask_b32_e32 v1, v1, v4, vcc
	v_sub_u32_e32 v4, v3, v2
	v_cndmask_b32_e32 v3, v3, v4, vcc
	v_add_u32_e32 v4, 1, v1
	v_cmp_ge_u32_e32 vcc, v3, v2
	v_add_u32_e32 v3, 1, v5
	s_nop 0
	v_cndmask_b32_e32 v1, v1, v4, vcc
	v_mul_lo_u32 v4, v2, v1
	v_add_u32_e32 v2, v4, v2
	v_cmp_ne_u32_e32 vcc, v3, v2
	s_waitcnt lgkmcnt(0)
	v_add_u32_e32 v1, 1, v1
	v_mul_lo_u32 v5, v1, v0
	v_readlane_b32 s14, v253, 6
	v_readlane_b32 s15, v253, 7
	v_mov_b32_e32 v0, 0
	s_add_u32 s14, s14, 0x7400
	s_addc_u32 s15, s15, 0
	s_mov_b32 s3, 0
	s_cbranch_vccnz .Ltb0_spin
	buffer_wbl2 sc1
	v_mov_b32_e32 v3, 1
	s_waitcnt vmcnt(0) lgkmcnt(0)
	s_nop 4
	global_atomic_add v0, v3, s[14:15]
.Ltb0_spin:
	s_sleep 1
	s_nop 4
	global_load_dword v1, v0, s[14:15] sc1
	s_add_i32 s3, s3, 1
	s_cmp_lt_u32 s3, 0x40000
	s_cbranch_scc0 .Ltb0_done
	s_waitcnt vmcnt(0)
	v_cmp_lt_u32_e32 vcc, v1, v5
	s_cbranch_vccnz .Ltb0_spin

.LBB0_474:
	s_or_b64 exec, exec, s[8:9]
	v_cvt_f32_u32_e32 v4, v2
	s_waitcnt vmcnt(0)
	v_readfirstlane_b32 s3, v3
	v_sub_u32_e32 v3, 0, v2
	v_rcp_iflag_f32_e32 v4, v4
	v_add_u32_e32 v5, s3, v1
	v_mul_f32_e32 v4, 0x4f7ffffe, v4
	v_cvt_u32_f32_e32 v4, v4
	v_mul_lo_u32 v1, v3, v4
	v_mul_hi_u32 v1, v4, v1
	v_add_u32_e32 v1, v4, v1
	v_mul_hi_u32 v1, v5, v1
	v_mul_lo_u32 v3, v1, v2
	v_sub_u32_e32 v3, v5, v3
	v_add_u32_e32 v4, 1, v1
	v_cmp_ge_u32_e32 vcc, v3, v2
	s_nop 1
	v_cndmask_b32_e32 v1, v1, v4, vcc
	v_sub_u32_e32 v4, v3, v2
	v_cndmask_b32_e32 v3, v3, v4, vcc
	v_add_u32_e32 v4, 1, v1
	v_cmp_ge_u32_e32 vcc, v3, v2
	v_add_u32_e32 v3, 1, v5
	s_nop 0
	v_cndmask_b32_e32 v1, v1, v4, vcc
	v_mul_lo_u32 v4, v2, v1
	v_add_u32_e32 v2, v4, v2
	v_cmp_ne_u32_e32 vcc, v3, v2
	s_waitcnt lgkmcnt(0)
	v_add_u32_e32 v1, 1, v1
	v_mul_lo_u32 v5, v1, v0
	v_readlane_b32 s12, v253, 6
	v_readlane_b32 s13, v253, 7
	v_mov_b32_e32 v0, 0
	s_add_u32 s12, s12, 0x7400
	s_addc_u32 s13, s13, 0
	s_mov_b32 s3, 0
	s_cbranch_vccnz .Ltb3_spin
	buffer_wbl2 sc1
	v_mov_b32_e32 v3, 1
	s_waitcnt vmcnt(0) lgkmcnt(0)
	s_nop 4
	global_atomic_add v0, v3, s[12:13]
.Ltb3_spin:
	s_sleep 1
	s_nop 4
	global_load_dword v1, v0, s[12:13] sc1
	s_add_i32 s3, s3, 1
	s_cmp_lt_u32 s3, 0x40000
	s_cbranch_scc0 .Ltb3_done
	s_waitcnt vmcnt(0)
	v_cmp_lt_u32_e32 vcc, v1, v5
	s_cbranch_vccnz .Ltb3_spin

.LBB0_561:
	s_or_b64 exec, exec, s[10:11]
	v_cvt_f32_u32_e32 v4, v2
	s_waitcnt vmcnt(0)
	v_readfirstlane_b32 s10, v3
	v_sub_u32_e32 v3, 0, v2
	v_rcp_iflag_f32_e32 v4, v4
	v_add_u32_e32 v5, s10, v1
	v_mul_f32_e32 v4, 0x4f7ffffe, v4
	v_cvt_u32_f32_e32 v4, v4
	v_mul_lo_u32 v1, v3, v4
	v_mul_hi_u32 v1, v4, v1
	v_add_u32_e32 v1, v4, v1
	v_mul_hi_u32 v1, v5, v1
	v_mul_lo_u32 v3, v1, v2
	v_sub_u32_e32 v3, v5, v3
	v_add_u32_e32 v4, 1, v1
	v_cmp_ge_u32_e32 vcc, v3, v2
	s_nop 1
	v_cndmask_b32_e32 v1, v1, v4, vcc
	v_sub_u32_e32 v4, v3, v2
	v_cndmask_b32_e32 v3, v3, v4, vcc
	v_add_u32_e32 v4, 1, v1
	v_cmp_ge_u32_e32 vcc, v3, v2
	v_add_u32_e32 v3, 1, v5
	s_nop 0
	v_cndmask_b32_e32 v1, v1, v4, vcc
	v_mul_lo_u32 v4, v2, v1
	v_add_u32_e32 v2, v4, v2
	v_cmp_ne_u32_e32 vcc, v3, v2
	s_waitcnt lgkmcnt(0)
	v_add_u32_e32 v1, 1, v1
	v_mul_lo_u32 v5, v1, v0
	v_readlane_b32 s14, v255, 34
	v_readlane_b32 s15, v255, 35
	v_mov_b32_e32 v0, 0
	s_mov_b32 s10, 0
	s_cbranch_vccnz .Ltb4_spin
	buffer_wbl2 sc1
	v_mov_b32_e32 v3, 1
	s_waitcnt vmcnt(0) lgkmcnt(0)
	s_nop 4
	global_atomic_add v0, v3, s[14:15]
.Ltb4_spin:
	s_sleep 1
	s_nop 4
	global_load_dword v1, v0, s[14:15] sc1
	s_add_i32 s10, s10, 1
	s_cmp_lt_u32 s10, 0x40000
	s_cbranch_scc0 .Ltb4_done
	s_waitcnt vmcnt(0)
	v_cmp_lt_u32_e32 vcc, v1, v5
	s_cbranch_vccnz .Ltb4_spin

.LBB0_647:
	s_or_b64 exec, exec, s[10:11]
	v_cvt_f32_u32_e32 v4, v2
	s_waitcnt vmcnt(0)
	v_readfirstlane_b32 s8, v3
	v_sub_u32_e32 v3, 0, v2
	v_rcp_iflag_f32_e32 v4, v4
	v_add_u32_e32 v5, s8, v1
	v_mul_f32_e32 v4, 0x4f7ffffe, v4
	v_cvt_u32_f32_e32 v4, v4
	v_mul_lo_u32 v1, v3, v4
	v_mul_hi_u32 v1, v4, v1
	v_add_u32_e32 v1, v4, v1
	v_mul_hi_u32 v1, v5, v1
	v_mul_lo_u32 v3, v1, v2
	v_sub_u32_e32 v3, v5, v3
	v_add_u32_e32 v4, 1, v1
	v_cmp_ge_u32_e32 vcc, v3, v2
	s_nop 1
	v_cndmask_b32_e32 v1, v1, v4, vcc
	v_sub_u32_e32 v4, v3, v2
	v_cndmask_b32_e32 v3, v3, v4, vcc
	v_add_u32_e32 v4, 1, v1
	v_cmp_ge_u32_e32 vcc, v3, v2
	v_add_u32_e32 v3, 1, v5
	s_nop 0
	v_cndmask_b32_e32 v1, v1, v4, vcc
	v_mul_lo_u32 v4, v2, v1
	v_add_u32_e32 v2, v4, v2
	v_cmp_ne_u32_e32 vcc, v3, v2
	s_waitcnt lgkmcnt(0)
	v_add_u32_e32 v1, 1, v1
	v_mul_lo_u32 v5, v1, v0
	v_readlane_b32 s14, v255, 34
	v_readlane_b32 s15, v255, 35
	v_mov_b32_e32 v0, 0
	s_mov_b32 s10, 0
	s_cbranch_vccnz .Ltb5_spin
	buffer_wbl2 sc1
	v_mov_b32_e32 v3, 1
	s_waitcnt vmcnt(0) lgkmcnt(0)
	s_nop 4
	global_atomic_add v0, v3, s[14:15]
